# attention wave priorities: QK block prio 1, P.V block prio 2, serial sections prio 0 (on top of GEMM hand-off)
# baseline (speedup 1.0000x reference)
.LBB0_940:
	s_setprio 1
	s_add_i32 s6, s80, 0xffffe000
	s_and_b32 s6, s6, 0x6000
	s_add_i32 s6, s6, 0
	s_add_i32 s6, s6, 0x14000
	v_add_u32_e32 v3, s6, v206
	v_add_u32_e32 v8, s6, v210
	ds_read_b128 v[4:7], v3
	ds_read_b128 v[8:11], v8 offset:4096
	s_waitcnt lgkmcnt(1)
	v_mfma_f32_32x32x16_bf16 v[132:147], v[4:7], v[176:179], v[82:97]
	v_add_u32_e32 v3, s6, v207
	ds_read_b128 v[12:15], v3
	v_add_u32_e32 v3, s6, v211
	ds_read_b128 v[216:219], v3 offset:4096
	v_add_f32_e32 v3, 0, v100
	v_add_f32_e32 v3, v101, v3
	v_add_f32_e32 v3, v102, v3
	v_add_f32_e32 v3, v103, v3
	v_cvt_pk_bf16_f32 v180, v100, v101
	v_cvt_pk_bf16_f32 v181, v102, v103
	s_waitcnt lgkmcnt(2)
	v_mfma_f32_32x32x16_bf16 v[148:163], v[8:11], v[176:179], v[82:97]
	v_add_f32_e32 v3, v104, v3
	v_add_f32_e32 v3, v105, v3
	v_add_f32_e32 v3, v106, v3
	v_add_f32_e32 v3, v107, v3
	v_cvt_pk_bf16_f32 v182, v104, v105
	v_cvt_pk_bf16_f32 v183, v106, v107
	s_waitcnt lgkmcnt(1)
	v_mfma_f32_32x32x16_bf16 v[132:147], v[12:15], v[172:175], v[132:147]
	v_add_u32_e32 v4, s6, v208
	v_add_u32_e32 v8, s6, v212
	ds_read_b128 v[4:7], v4
	ds_read_b128 v[220:223], v8 offset:4096
	v_add_f32_e32 v3, v108, v3
	v_add_f32_e32 v3, v109, v3
	v_add_f32_e32 v3, v110, v3
	v_add_f32_e32 v3, v111, v3
	v_cvt_pk_bf16_f32 v12, v108, v109
	v_cvt_pk_bf16_f32 v13, v110, v111
	s_waitcnt lgkmcnt(2)
	v_mfma_f32_32x32x16_bf16 v[148:163], v[216:219], v[172:175], v[148:163]
	v_add_f32_e32 v3, v112, v3
	v_add_f32_e32 v3, v113, v3
	v_add_f32_e32 v3, v114, v3
	v_add_f32_e32 v3, v115, v3
	v_cvt_pk_bf16_f32 v14, v112, v113
	v_cvt_pk_bf16_f32 v15, v114, v115
	s_waitcnt lgkmcnt(1)
	v_mfma_f32_32x32x16_bf16 v[132:147], v[4:7], v[168:171], v[132:147]
	v_add_u32_e32 v8, s6, v209
	v_add_u32_e32 v9, s6, v213
	ds_read_b128 v[216:219], v8
	ds_read_b128 v[224:227], v9 offset:4096
	v_add_f32_e32 v3, v116, v3
	v_add_f32_e32 v3, v117, v3
	v_add_f32_e32 v3, v118, v3
	v_add_f32_e32 v3, v119, v3
	v_cvt_pk_bf16_f32 v8, v116, v117
	v_cvt_pk_bf16_f32 v9, v118, v119
	s_waitcnt lgkmcnt(2)
	v_mfma_f32_32x32x16_bf16 v[148:163], v[220:223], v[168:171], v[148:163]
	v_add_f32_e32 v3, v120, v3
	v_add_f32_e32 v3, v121, v3
	v_add_f32_e32 v3, v122, v3
	v_add_f32_e32 v3, v123, v3
	v_cvt_pk_bf16_f32 v10, v120, v121
	v_cvt_pk_bf16_f32 v11, v122, v123
	s_waitcnt lgkmcnt(1)
	v_mfma_f32_32x32x16_bf16 v[132:147], v[216:219], v[164:167], v[132:147]
	v_add_f32_e32 v3, v124, v3
	v_add_f32_e32 v3, v125, v3
	v_add_f32_e32 v3, v126, v3
	v_add_f32_e32 v3, v127, v3
	v_cvt_pk_bf16_f32 v4, v124, v125
	v_cvt_pk_bf16_f32 v5, v126, v127
	s_waitcnt lgkmcnt(0)
	v_mfma_f32_32x32x16_bf16 v[148:163], v[224:227], v[164:167], v[148:163]
	v_add_f32_e32 v3, v128, v3
	v_add_f32_e32 v3, v129, v3
	v_add_f32_e32 v3, v130, v3
	v_add_f32_e32 v3, v131, v3
	v_cvt_pk_bf16_f32 v6, v128, v129
	v_cvt_pk_bf16_f32 v7, v130, v131
	s_mul_hi_u32 s6, s81, 0xcccccccd
	s_lshr_b32 s6, s6, 2
	s_mul_i32 s6, s6, 0x14000
	v_subrev_u32_e32 v243, s6, v215
	ds_read_b64_tr_b16 v[228:229], v243 offset:0
	ds_read_b64_tr_b16 v[230:231], v243 offset:0x800
	ds_read_b64_tr_b16 v[232:233], v243 offset:0x200
	ds_read_b64_tr_b16 v[234:235], v243 offset:0xa00
	ds_read_b64_tr_b16 v[236:237], v243 offset:0x400
	ds_read_b64_tr_b16 v[238:239], v243 offset:0xc00
	ds_read_b64_tr_b16 v[240:241], v243 offset:0x600
	ds_read_b64_tr_b16 v[242:243], v243 offset:0xe00
	s_nop 0
	v_cmp_ge_f32_e32 vcc, s38, v3
	s_cmp_eq_u64 vcc, exec
	s_cbranch_scc0 .LBB0_958

.LBB0_946:
	s_setprio 2
	s_mul_hi_u32 s6, s81, 0xcccccccd
	s_lshr_b32 s6, s6, 2
	s_mul_i32 s6, s6, 0x14000
	v_subrev_u32_e32 v16, s6, v215
	s_cmp_lg_u32 0, -1
	s_cselect_b32 s6, 0, 0
	v_add_u32_e32 v16, s6, v16
	ds_read_b64_tr_b16 v[116:117], v16 offset:0x1000
	ds_read_b64_tr_b16 v[118:119], v16 offset:0x1800
	ds_read_b64_tr_b16 v[120:121], v16 offset:0x1200
	ds_read_b64_tr_b16 v[122:123], v16 offset:0x1a00
	ds_read_b64_tr_b16 v[124:125], v16 offset:0x1400
	ds_read_b64_tr_b16 v[126:127], v16 offset:0x1c00
	ds_read_b64_tr_b16 v[128:129], v16 offset:0x1600
	ds_read_b64_tr_b16 v[130:131], v16 offset:0x1e00
	s_waitcnt lgkmcnt(8)
	s_nop 0
	v_mfma_f32_32x32x16_bf16 v[66:81], v[228:231], v[180:183], v[66:81]
	v_exp_f32_e32 v132, v132
	v_exp_f32_e32 v133, v133
	v_mfma_f32_32x32x16_bf16 v[50:65], v[232:235], v[180:183], v[50:65]
	v_exp_f32_e32 v134, v134
	v_exp_f32_e32 v135, v135
	v_mfma_f32_32x32x16_bf16 v[34:49], v[236:239], v[180:183], v[34:49]
	v_exp_f32_e32 v136, v136
	v_exp_f32_e32 v137, v137
	v_mfma_f32_32x32x16_bf16 v[18:33], v[240:243], v[180:183], v[18:33]
	v_exp_f32_e32 v138, v138
	v_exp_f32_e32 v139, v139
	ds_read_b64_tr_b16 v[100:101], v16 offset:0x2000
	ds_read_b64_tr_b16 v[102:103], v16 offset:0x2800
	ds_read_b64_tr_b16 v[104:105], v16 offset:0x2200
	ds_read_b64_tr_b16 v[106:107], v16 offset:0x2a00
	ds_read_b64_tr_b16 v[108:109], v16 offset:0x2400
	ds_read_b64_tr_b16 v[110:111], v16 offset:0x2c00
	ds_read_b64_tr_b16 v[112:113], v16 offset:0x2600
	ds_read_b64_tr_b16 v[114:115], v16 offset:0x2e00
	s_waitcnt lgkmcnt(8)
	v_mfma_f32_32x32x16_bf16 v[66:81], v[116:119], v[12:15], v[66:81]
	v_exp_f32_e32 v140, v140
	v_exp_f32_e32 v141, v141
	v_mfma_f32_32x32x16_bf16 v[50:65], v[120:123], v[12:15], v[50:65]
	v_exp_f32_e32 v142, v142
	v_exp_f32_e32 v143, v143
	v_mfma_f32_32x32x16_bf16 v[34:49], v[124:127], v[12:15], v[34:49]
	v_exp_f32_e32 v144, v144
	v_exp_f32_e32 v145, v145
	v_mfma_f32_32x32x16_bf16 v[18:33], v[128:131], v[12:15], v[18:33]
	v_exp_f32_e32 v146, v146
	v_exp_f32_e32 v147, v147
	ds_read_b64_tr_b16 v[12:13], v16 offset:0x3000
	ds_read_b64_tr_b16 v[14:15], v16 offset:0x3800
	ds_read_b64_tr_b16 v[116:117], v16 offset:0x3200
	ds_read_b64_tr_b16 v[118:119], v16 offset:0x3a00
	ds_read_b64_tr_b16 v[120:121], v16 offset:0x3400
	ds_read_b64_tr_b16 v[122:123], v16 offset:0x3c00
	ds_read_b64_tr_b16 v[124:125], v16 offset:0x3600
	ds_read_b64_tr_b16 v[126:127], v16 offset:0x3e00
	s_waitcnt lgkmcnt(8)
	v_mfma_f32_32x32x16_bf16 v[66:81], v[100:103], v[8:11], v[66:81]
	v_exp_f32_e32 v148, v148
	v_exp_f32_e32 v149, v149
	v_mfma_f32_32x32x16_bf16 v[50:65], v[104:107], v[8:11], v[50:65]
	v_exp_f32_e32 v150, v150
	v_exp_f32_e32 v151, v151
	v_mfma_f32_32x32x16_bf16 v[34:49], v[108:111], v[8:11], v[34:49]
	v_exp_f32_e32 v152, v152
	v_exp_f32_e32 v153, v153
	v_mfma_f32_32x32x16_bf16 v[18:33], v[112:115], v[8:11], v[18:33]
	v_exp_f32_e32 v154, v154
	v_exp_f32_e32 v155, v155
	s_waitcnt lgkmcnt(0)
	v_mfma_f32_32x32x16_bf16 v[66:81], v[12:15], v[4:7], v[66:81]
	v_exp_f32_e32 v156, v156
	v_exp_f32_e32 v157, v157
	v_mfma_f32_32x32x16_bf16 v[50:65], v[116:119], v[4:7], v[50:65]
	v_exp_f32_e32 v158, v158
	v_exp_f32_e32 v159, v159
	v_mfma_f32_32x32x16_bf16 v[34:49], v[120:123], v[4:7], v[34:49]
	v_exp_f32_e32 v160, v160
	v_exp_f32_e32 v161, v161
	v_mfma_f32_32x32x16_bf16 v[18:33], v[124:127], v[4:7], v[18:33]
	v_exp_f32_e32 v162, v162
	v_exp_f32_e32 v163, v163
	s_setprio 0

.LBB0_950:
	s_setprio 1
	v_add_f32_e32 v16, v3, v184
	s_and_b32 s17, s80, 0x6000
	s_add_i32 s17, s17, 0
	s_add_i32 s17, s17, 0x14000
	v_add_u32_e32 v3, s17, v206
	v_add_u32_e32 v8, s17, v210
	ds_read_b128 v[4:7], v3
	ds_read_b128 v[8:11], v8 offset:4096
	s_waitcnt lgkmcnt(1)
	v_mfma_f32_32x32x16_bf16 v[100:115], v[4:7], v[176:179], v[82:97]
	v_add_u32_e32 v3, s17, v207
	ds_read_b128 v[12:15], v3
	v_add_u32_e32 v3, s17, v211
	ds_read_b128 v[216:219], v3 offset:4096
	v_add_f32_e32 v3, 0, v132
	v_add_f32_e32 v3, v133, v3
	v_add_f32_e32 v3, v134, v3
	v_add_f32_e32 v3, v135, v3
	v_cvt_pk_bf16_f32 v180, v132, v133
	v_cvt_pk_bf16_f32 v181, v134, v135
	s_waitcnt lgkmcnt(2)
	v_mfma_f32_32x32x16_bf16 v[116:131], v[8:11], v[176:179], v[82:97]
	v_add_f32_e32 v3, v136, v3
	v_add_f32_e32 v3, v137, v3
	v_add_f32_e32 v3, v138, v3
	v_add_f32_e32 v3, v139, v3
	v_cvt_pk_bf16_f32 v182, v136, v137
	v_cvt_pk_bf16_f32 v183, v138, v139
	s_waitcnt lgkmcnt(1)
	v_mfma_f32_32x32x16_bf16 v[100:115], v[12:15], v[172:175], v[100:115]
	v_add_u32_e32 v4, s17, v208
	v_add_u32_e32 v8, s17, v212
	ds_read_b128 v[4:7], v4
	ds_read_b128 v[220:223], v8 offset:4096
	v_add_f32_e32 v3, v140, v3
	v_add_f32_e32 v3, v141, v3
	v_add_f32_e32 v3, v142, v3
	v_add_f32_e32 v3, v143, v3
	v_cvt_pk_bf16_f32 v12, v140, v141
	v_cvt_pk_bf16_f32 v13, v142, v143
	s_waitcnt lgkmcnt(2)
	v_mfma_f32_32x32x16_bf16 v[116:131], v[216:219], v[172:175], v[116:131]
	v_add_f32_e32 v3, v144, v3
	v_add_f32_e32 v3, v145, v3
	v_add_f32_e32 v3, v146, v3
	v_add_f32_e32 v3, v147, v3
	v_cvt_pk_bf16_f32 v14, v144, v145
	v_cvt_pk_bf16_f32 v15, v146, v147
	s_waitcnt lgkmcnt(1)
	v_mfma_f32_32x32x16_bf16 v[100:115], v[4:7], v[168:171], v[100:115]
	v_add_u32_e32 v8, s17, v209
	v_add_u32_e32 v9, s17, v213
	ds_read_b128 v[216:219], v8
	ds_read_b128 v[224:227], v9 offset:4096
	v_add_f32_e32 v3, v148, v3
	v_add_f32_e32 v3, v149, v3
	v_add_f32_e32 v3, v150, v3
	v_add_f32_e32 v3, v151, v3
	v_cvt_pk_bf16_f32 v8, v148, v149
	v_cvt_pk_bf16_f32 v9, v150, v151
	s_waitcnt lgkmcnt(2)
	v_mfma_f32_32x32x16_bf16 v[116:131], v[220:223], v[168:171], v[116:131]
	v_add_f32_e32 v3, v152, v3
	v_add_f32_e32 v3, v153, v3
	v_add_f32_e32 v3, v154, v3
	v_add_f32_e32 v3, v155, v3
	v_cvt_pk_bf16_f32 v10, v152, v153
	v_cvt_pk_bf16_f32 v11, v154, v155
	s_waitcnt lgkmcnt(1)
	v_mfma_f32_32x32x16_bf16 v[100:115], v[216:219], v[164:167], v[100:115]
	v_add_f32_e32 v3, v156, v3
	v_add_f32_e32 v3, v157, v3
	v_add_f32_e32 v3, v158, v3
	v_add_f32_e32 v3, v159, v3
	v_cvt_pk_bf16_f32 v4, v156, v157
	v_cvt_pk_bf16_f32 v5, v158, v159
	s_waitcnt lgkmcnt(0)
	v_mfma_f32_32x32x16_bf16 v[116:131], v[224:227], v[164:167], v[116:131]
	v_add_f32_e32 v3, v160, v3
	v_add_f32_e32 v3, v161, v3
	v_add_f32_e32 v3, v162, v3
	v_add_f32_e32 v17, v163, v3
	v_cvt_pk_bf16_f32 v6, v160, v161
	v_cvt_pk_bf16_f32 v7, v162, v163
	s_mul_hi_u32 s17, s92, 0xcccccccd
	s_lshr_b32 s17, s17, 2
	s_mul_i32 s17, s17, 0x14000
	v_subrev_u32_e32 v243, s17, v214
	ds_read_b64_tr_b16 v[228:229], v243 offset:0
	ds_read_b64_tr_b16 v[230:231], v243 offset:0x800
	ds_read_b64_tr_b16 v[232:233], v243 offset:0x200
	ds_read_b64_tr_b16 v[234:235], v243 offset:0xa00
	ds_read_b64_tr_b16 v[236:237], v243 offset:0x400
	ds_read_b64_tr_b16 v[238:239], v243 offset:0xc00
	ds_read_b64_tr_b16 v[240:241], v243 offset:0x600
	ds_read_b64_tr_b16 v[242:243], v243 offset:0xe00
	s_nop 0
	v_cmp_ge_f32_e32 vcc, s38, v17
	s_cmp_eq_u64 vcc, exec
	s_cbranch_scc0 .LBB0_960

.LBB0_955:
.LBB0_956:
	s_setprio 2
	s_mul_hi_u32 s10, s92, 0xcccccccd
	s_lshr_b32 s10, s10, 2
	v_pk_add_f32 v[184:185], v[16:17], v[16:17] op_sel:[1,0] op_sel_hi:[0,1]
	s_mul_i32 s10, s10, 0x14000
	v_subrev_u32_e32 v3, s10, v214
	s_cmp_lg_u32 0, -1
	s_cselect_b32 s10, 0, 0
	v_add_u32_e32 v3, s10, v3
	ds_read_b64_tr_b16 v[148:149], v3 offset:0x1000
	ds_read_b64_tr_b16 v[150:151], v3 offset:0x1800
	ds_read_b64_tr_b16 v[152:153], v3 offset:0x1200
	ds_read_b64_tr_b16 v[154:155], v3 offset:0x1a00
	ds_read_b64_tr_b16 v[156:157], v3 offset:0x1400
	ds_read_b64_tr_b16 v[158:159], v3 offset:0x1c00
	ds_read_b64_tr_b16 v[160:161], v3 offset:0x1600
	ds_read_b64_tr_b16 v[162:163], v3 offset:0x1e00
	s_waitcnt lgkmcnt(8)
	s_nop 0
	v_mfma_f32_32x32x16_bf16 v[66:81], v[228:231], v[180:183], v[66:81]
	v_exp_f32_e32 v100, v100
	v_exp_f32_e32 v101, v101
	v_mfma_f32_32x32x16_bf16 v[50:65], v[232:235], v[180:183], v[50:65]
	v_exp_f32_e32 v102, v102
	v_exp_f32_e32 v103, v103
	v_mfma_f32_32x32x16_bf16 v[34:49], v[236:239], v[180:183], v[34:49]
	v_exp_f32_e32 v104, v104
	v_exp_f32_e32 v105, v105
	v_mfma_f32_32x32x16_bf16 v[18:33], v[240:243], v[180:183], v[18:33]
	v_exp_f32_e32 v106, v106
	v_exp_f32_e32 v107, v107
	ds_read_b64_tr_b16 v[132:133], v3 offset:0x2000
	ds_read_b64_tr_b16 v[134:135], v3 offset:0x2800
	ds_read_b64_tr_b16 v[136:137], v3 offset:0x2200
	ds_read_b64_tr_b16 v[138:139], v3 offset:0x2a00
	ds_read_b64_tr_b16 v[140:141], v3 offset:0x2400
	ds_read_b64_tr_b16 v[142:143], v3 offset:0x2c00
	ds_read_b64_tr_b16 v[144:145], v3 offset:0x2600
	ds_read_b64_tr_b16 v[146:147], v3 offset:0x2e00
	s_waitcnt lgkmcnt(8)
	v_mfma_f32_32x32x16_bf16 v[66:81], v[148:151], v[12:15], v[66:81]
	v_exp_f32_e32 v108, v108
	v_exp_f32_e32 v109, v109
	v_mfma_f32_32x32x16_bf16 v[50:65], v[152:155], v[12:15], v[50:65]
	v_exp_f32_e32 v110, v110
	v_exp_f32_e32 v111, v111
	v_mfma_f32_32x32x16_bf16 v[34:49], v[156:159], v[12:15], v[34:49]
	v_exp_f32_e32 v112, v112
	v_exp_f32_e32 v113, v113
	v_mfma_f32_32x32x16_bf16 v[18:33], v[160:163], v[12:15], v[18:33]
	v_exp_f32_e32 v114, v114
	v_exp_f32_e32 v115, v115
	ds_read_b64_tr_b16 v[12:13], v3 offset:0x3000
	ds_read_b64_tr_b16 v[14:15], v3 offset:0x3800
	ds_read_b64_tr_b16 v[148:149], v3 offset:0x3200
	ds_read_b64_tr_b16 v[150:151], v3 offset:0x3a00
	ds_read_b64_tr_b16 v[152:153], v3 offset:0x3400
	ds_read_b64_tr_b16 v[154:155], v3 offset:0x3c00
	ds_read_b64_tr_b16 v[156:157], v3 offset:0x3600
	ds_read_b64_tr_b16 v[158:159], v3 offset:0x3e00
	s_waitcnt lgkmcnt(8)
	v_mfma_f32_32x32x16_bf16 v[66:81], v[132:135], v[8:11], v[66:81]
	v_exp_f32_e32 v116, v116
	v_exp_f32_e32 v117, v117
	v_mfma_f32_32x32x16_bf16 v[50:65], v[136:139], v[8:11], v[50:65]
	v_exp_f32_e32 v118, v118
	v_exp_f32_e32 v119, v119
	v_mfma_f32_32x32x16_bf16 v[34:49], v[140:143], v[8:11], v[34:49]
	v_exp_f32_e32 v120, v120
	v_exp_f32_e32 v121, v121
	v_mfma_f32_32x32x16_bf16 v[18:33], v[144:147], v[8:11], v[18:33]
	v_exp_f32_e32 v122, v122
	v_exp_f32_e32 v123, v123
	s_waitcnt lgkmcnt(0)
	v_mfma_f32_32x32x16_bf16 v[66:81], v[12:15], v[4:7], v[66:81]
	v_exp_f32_e32 v124, v124
	v_exp_f32_e32 v125, v125
	v_mfma_f32_32x32x16_bf16 v[50:65], v[148:151], v[4:7], v[50:65]
	v_exp_f32_e32 v126, v126
	v_exp_f32_e32 v127, v127
	v_mfma_f32_32x32x16_bf16 v[34:49], v[152:155], v[4:7], v[34:49]
	v_exp_f32_e32 v128, v128
	v_exp_f32_e32 v129, v129
	v_mfma_f32_32x32x16_bf16 v[18:33], v[156:159], v[4:7], v[18:33]
	v_exp_f32_e32 v130, v130
	v_exp_f32_e32 v131, v131
	s_setprio 0
